# phase 1: layer-0 weight transposes run only on the 80 workgroups that have a single GEMM tile (was: 192 workgroups incl. those with two tiles)
# speedup vs baseline: 1.0003x; 1.0003x over previous
.LBB0_276:
	s_cmpk_lt_i32 s3, 0xb0
	s_waitcnt vmcnt(0) lgkmcnt(0)
	s_barrier
	s_cbranch_scc1 .LBB0_411
	s_sub_i32 s36, s2, 0xb0
	s_add_i32 s44, s3, 0x250
	s_cmpk_lt_u32 s3, 0x9b0
	s_cselect_b64 s[12:13], -1, 0
	s_cmpk_gt_u32 s3, 0x9af
	s_cbranch_scc1 .LBB0_282
	s_add_u32 s14, s22, 0x110
	s_addc_u32 s15, s23, 0
	s_add_u32 s4, s20, 0x2000000
	s_addc_u32 s5, s21, 0
	s_add_u32 s24, s22, 0x108
	s_addc_u32 s25, s23, 0
	s_add_u32 s26, s20, 0x1000000
	s_addc_u32 s27, s21, 0
	s_add_u32 s16, s22, 0x80
	s_addc_u32 s17, s23, 0
	s_add_u32 s18, s20, 0xc00000
	s_addc_u32 s19, s21, 0
	s_cmpk_gt_u32 s3, 0x1af
	s_cbranch_scc0 .LBB0_283
	s_cmpk_gt_u32 s3, 0x5af
	s_cbranch_scc0 .LBB0_295
	s_add_i32 s6, s3, 0xfffffa50
	s_lshr_b32 s33, s6, 4
	s_cbranch_execz .LBB0_296
	s_mov_b32 s28, 15
	s_movk_i32 s39, 0x400
	s_movk_i32 s38, 0x1000
	s_mov_b64 s[8:9], s[14:15]
	s_mov_b64 s[6:7], s[4:5]
	s_cbranch_execz .LBB0_284
	s_branch .LBB0_285

.LBB0_283:
.LBB0_284:
	s_sub_i32 s6, s3, 0xb0
	s_lshr_b32 s33, s6, 4
	s_movk_i32 s39, 0x400
	s_mov_b32 s28, 15
	s_movk_i32 s38, 0x400
	s_mov_b64 s[6:7], s[18:19]
	s_mov_b64 s[8:9], s[16:17]

.LBB0_295:
.LBB0_296:
	s_add_i32 s6, s3, 0xfffffe50
	s_lshr_b32 s33, s6, 6
	s_mov_b32 s28, 63
	s_movk_i32 s39, 0x1000
	s_movk_i32 s38, 0x400
	s_mov_b64 s[8:9], s[24:25]
	s_mov_b64 s[6:7], s[26:27]
	s_cbranch_execz .LBB0_284
	s_branch .LBB0_285

.LBB0_334:
	v_add_u32_e32 v37, 0x200, v148
	s_lshl_b32 s58, s36, 2
	v_ashrrev_i32_e32 v42, 4, v148
	s_movk_i32 s12, 0x104
	v_ashrrev_i32_e32 v43, 4, v37
	v_mul_lo_u32 v36, v42, s12
	v_mul_lo_u32 v37, v43, s12
	s_add_u32 s12, s22, 0x110
	s_addc_u32 s13, s23, 0
	s_add_u32 s14, s20, 0x2000000
	s_addc_u32 s15, s21, 0
	s_add_u32 s16, s22, 0x108
	s_addc_u32 s17, s23, 0
	s_add_u32 s18, s20, 0x1000000
	s_addc_u32 s19, s21, 0
	s_add_u32 s24, s22, 0x80
	s_addc_u32 s25, s23, 0
	s_add_u32 s26, s20, 0xc00000
	v_lshlrev_b32_e32 v16, 2, v148
	s_addc_u32 s27, s21, 0
	v_and_b32_e32 v40, 60, v16
	v_lshlrev_b32_e32 v16, 3, v148
	s_add_u32 s22, s22, 0x78
	v_ashrrev_i32_e32 v41, 3, v148
	v_and_b32_e32 v18, 56, v16
	s_addc_u32 s23, s23, 0
	s_lshl_b32 s28, s2, 1
	v_lshlrev_b32_e32 v17, 2, v40
	v_lshlrev_b32_e32 v19, 2, v41
	v_mul_u32_u24_e32 v38, 0x104, v18
	s_add_i32 s59, s58, s28
	s_mul_i32 s28, s2, 3
	s_add_i32 s60, s58, s28
	s_add_i32 s2, s58, s2
	v_add_u32_e32 v44, v17, v36
	v_add_u32_e32 v45, v17, v37
	v_add_u32_e32 v58, v19, v38
	v_mov_b32_e32 v16, 0
	s_addk_i32 s59, 0xfea0
	s_addk_i32 s60, 0xfdf0
	s_sub_i32 s2, s2, 0xb0
	v_add_u32_e32 v46, 0x4100, v44
	v_add_u32_e32 v47, 0x4108, v44
	v_add_u32_e32 v48, 0x4100, v45
	v_add_u32_e32 v49, 0x4108, v45
	v_add_u32_e32 v50, 0x8200, v44
	v_add_u32_e32 v51, 0x8208, v44
	v_add_u32_e32 v52, 0x8200, v45
	v_add_u32_e32 v53, 0x8208, v45
	v_add_u32_e32 v54, 0xc300, v44
	v_add_u32_e32 v55, 0xc308, v44
	v_add_u32_e32 v56, 0xc300, v45
	v_add_u32_e32 v57, 0xc308, v45
	v_lshlrev_b32_e32 v36, 1, v18
	v_add_u32_e32 v59, 0x400, v58
	v_add_u32_e32 v60, 0x4600, v58
	v_add_u32_e32 v61, 0x4400, v58
	v_add_u32_e32 v62, 0x4200, v58
	v_add_u32_e32 v63, 0x4000, v58
	v_add_u32_e32 v64, 0x8800, v58
	v_add_u32_e32 v65, 0x8400, v58
	v_add_u32_e32 v66, 0x8000, v58
	v_add_u32_e32 v67, 0xc800, v58
	v_add_u32_e32 v68, 0xc600, v58
	v_add_u32_e32 v69, 0xc400, v58
	v_add_u32_e32 v70, 0xc200, v58
	s_mov_b32 s75, s55
	s_mov_b32 s74, s54
	s_mov_b32 s77, s57
	s_mov_b64 s[28:29], s[6:7]
	s_mov_b32 s63, s38
	s_mov_b32 s64, s39
	s_mov_b32 s61, s33
	s_mov_b32 s62, s3
	s_mov_b32 s76, s56
	s_mov_b64 s[34:35], s[8:9]
	s_mov_b32 s68, s48
	s_mov_b32 s69, s49
	s_mov_b32 s66, s46
	s_mov_b32 s67, s47
	s_mov_b64 s[40:41], s[4:5]
	s_mov_b64 s[36:37], s[10:11]
	s_mov_b32 s72, s52
	s_mov_b32 s73, s53
	s_mov_b32 s70, s50
	s_mov_b32 s71, s51
	s_branch .LBB0_336
